# dilated attention: two register sets for the K/V tile prefetch (loads at step top, store at step end, two steps of latency budget)
# baseline (speedup 1.0000x reference)
; #define LAS __attribute__((address_space(3)))
; #define C_LOADP(p_) do { const bf16_t* q_ = (p_); rka = ldg16(q_ + kvlane); rva = ldg16(q_ + (size_t)16 * T * 64 + kvlane); rkb = ldg16(q_ + (size_t)T * 64 + kvlane); rvb = ldg16(q_ + (size_t)17 * T * 64 + kvlane); } while (0)
; __device__ __forceinline__ void c_phase(const bf16_t* Z, bf16_t* MIX, float* LSE, ldsp lds, int pi, int bx, int G, unsigned& gt, int wave0, int ucount) {
;     int tid_; asm volatile("v_mbcnt_lo_u32_b32 %0, -1, 0\n\tv_mbcnt_hi_u32_b32 %0, -1, %0" : "=&v"(tid_)); tid_ += wave0 * 64; const int tid = tid_, lane = tid & 63, w = __builtin_amdgcn_readfirstlane(tid >> 6), r32 = lane & 31, hi = lane >> 5;
;     const int hsel = w >> 2, gq = (w < 4) ? w : 7 - w, key = tid >> 3, ch = tid & 7;
;     const int ldil = 2 * pi, dil = 1 << ldil, lnb = 5 - ldil;
;     LAS float* wsf = (LAS float*)(lds + LDS_WSF) + w * 64;
;     const size_t tstride = (size_t)64 * dil * 64;
;     const unsigned kvlane = (unsigned)(key * dil * 64 + ch * 8), qlane = (unsigned)(r32 * dil * 64), olane = (unsigned)((lane >> 3) * dil * 1024 + (lane & 7) * 8), llane = (unsigned)(r32 * dil * 16);
;     ...
;     const u32x4 z4 = {0u, 0u, 0u, 0u};
;     u32x4 rka = z4, rva = z4, rkb = z4, rvb = z4;
;     const int per = (ucount + G - 1) / G, uend = (bx + 1) * per < ucount ? (bx + 1) * per : ucount;
;     int u = bx * per;
;     if (u >= uend) return;
;     {   C_DEC(u, b, hp, rs, blk); const int kt0 = blk >= 1 ? 2 * blk - 2 : 0; const bf16_t* kvp = C_KVP(b, hp, rs);
;         C_LOADP(kvp + kt0 * tstride);
;         { const ldsp b0 = lds + (gt & 1u) * 32768; tile_store(b0, rka, rva, key, ch); tile_store(b0 + 16384, rkb, rvb, key, ch); }
;         C_LOADP(kvp + (kt0 + 1) * tstride);
.LBB0_1032:
	s_mov_b64 s[0:1], s[90:91]
	v_mbcnt_lo_u32_b32 v18, -1, 0
	v_mbcnt_hi_u32_b32 v18, -1, v18
	s_andn2_b64 vcc, exec, s[66:67]
	v_add_u32_e32 v19, s93, v18
	s_nop 0
	v_readfirstlane_b32 s2, v19
	s_cbranch_vccnz .LBB0_1096
	s_add_u32 s4, s0, 0x200000
	s_addc_u32 s29, s1, 0
	s_add_u32 s5, s0, 0x4800000
	v_writelane_b32 v255, s5, 18
	s_addc_u32 s5, s1, 0
	s_add_u32 s80, s0, 0xc800000
	s_addc_u32 s81, s1, 0
	s_and_b32 s0, s2, 0x3fffffc0
	s_lshl_b32 s0, s0, 2
	v_writelane_b32 v255, s5, 19
	s_lshl_b32 s31, s38, 1
	s_add_i32 s5, s0, 0
	s_ashr_i32 s8, s2, 6
	s_ashr_i32 s30, s2, 8
	s_sub_i32 s33, 5, s31
	s_add_i32 s5, s5, 0x23000
	s_sub_i32 s0, 7, s8
	s_cmp_lt_i32 s8, 4
	s_cselect_b32 s2, s8, s0
	s_lshl_b32 s0, -1, s33
	v_readlane_b32 s28, v255, 6
	s_not_b32 s34, s0
	s_andn2_b32 s0, s28, s0
	s_ashr_i32 s1, s28, s33
	s_lshl_b32 s6, -1, s31
	v_readlane_b32 s12, v254, 18
	s_andn2_b32 s12, s1, s6
	s_lshl_b32 s1, s0, 1
	s_not_b32 s35, s6
	s_add_i32 s1, s1, -2
	s_cmp_lg_u32 s0, 0
	v_readlane_b32 s6, v255, 7
	v_readlane_b32 s13, v254, 19
	s_cselect_b32 s0, s1, 0
	v_readlane_b32 s7, v255, 8
	s_add_u32 s1, s80, s6
	s_addc_u32 s6, s81, s7
	s_lshl_b64 s[10:11], s[12:13], 7
	s_add_u32 s7, s1, s10
	s_addc_u32 s6, s6, s11
	s_mov_b32 s1, s13
	s_add_i32 s72, s31, 12
	v_ashrrev_i32_e32 v19, 3, v19
	v_and_b32_e32 v44, 7, v18
	s_lshl_b64 s[10:11], s[0:1], s72
	v_lshlrev_b32_e32 v20, s31, v19
	v_lshlrev_b32_e32 v21, 3, v44
	s_lshl_b64 s[10:11], s[10:11], 1
	v_lshl_or_b32 v184, v20, 6, v21
	s_add_u32 s10, s7, s10
	v_mov_b32_e32 v185, v177
	s_addc_u32 s11, s6, s11
	v_lshlrev_b64 v[36:37], 1, v[184:185]
	v_lshl_add_u64 v[32:33], s[10:11], 0, v[36:37]
	global_load_dwordx4 v[20:23], v[32:33], off
	s_mov_b32 s9, 0x800000
	v_add_co_u32_e32 v24, vcc, s9, v32
	s_mov_b32 s10, 0x80000
	s_nop 0
	v_addc_co_u32_e32 v25, vcc, 0, v33, vcc
	v_add_co_u32_e32 v28, vcc, s10, v32
	s_mov_b32 s11, 0x880000
	s_nop 0
	v_addc_co_u32_e32 v29, vcc, 0, v33, vcc
	global_load_dwordx4 v[24:27], v[24:25], off
	v_add_co_u32_e32 v32, vcc, s11, v32
	global_load_dwordx4 v[28:31], v[28:29], off
	s_nop 0
	v_addc_co_u32_e32 v33, vcc, 0, v33, vcc
	global_load_dwordx4 v[32:35], v[32:33], off
	s_lshl_b32 s1, s3, 15
	s_and_b32 s1, s1, 0x8000
	v_lshlrev_b32_e32 v202, 10, v44
	v_lshlrev_b32_e32 v44, 5, v44
	v_lshlrev_b32_e32 v45, 4, v19
	s_add_i32 s1, s1, 0
	v_xor_b32_e32 v203, v45, v44
	v_lshlrev_b32_e32 v19, 6, v19
	v_add3_u32 v44, s1, v202, v203
	v_and_b32_e32 v204, 0x1000, v202
	v_and_b32_e32 v205, 0xfffffc00, v19
	v_readlane_b32 s14, v254, 20
	v_readlane_b32 s15, v254, 21
	s_or_b32 s12, s0, 1
	v_readlane_b32 s16, v254, 22
	v_readlane_b32 s17, v254, 23
	v_readlane_b32 s18, v254, 24
	v_readlane_b32 s19, v254, 25
	v_readlane_b32 s20, v254, 26
	v_readlane_b32 s21, v254, 27
	v_readlane_b32 s22, v254, 28
	v_readlane_b32 s23, v254, 29
	v_readlane_b32 s24, v254, 30
	v_readlane_b32 s25, v254, 31
	v_readlane_b32 s26, v254, 32
	v_readlane_b32 s27, v254, 33
	v_and_b32_e32 v206, 0x3c0, v19
	v_lshlrev_b32_e32 v19, 4, v18
	v_and_b32_e32 v207, 48, v19
	v_and_b32_e32 v17, 31, v18
	v_and_b32_e32 v38, 63, v18
	v_lshlrev_b32_e32 v40, s31, v17
	v_bfe_u32 v43, v18, 5, 1
	v_lshlrev_b32_e32 v176, 7, v40
	v_writelane_b32 v255, s38, 20
	v_lshlrev_b32_e32 v186, 4, v43
	v_mov_b32_e32 v187, v177
	v_lshlrev_b32_e32 v41, 3, v18
	v_bfe_u32 v39, v18, 3, 3
	v_and_b32_e32 v42, 56, v41
	v_and_b32_e32 v250, 0xc0, v19
	v_lshlrev_b32_e32 v209, 2, v43
	v_lshlrev_b32_e32 v16, s31, v39
	v_or_b32_e32 v211, 1, v209
	v_lshl_or_b32 v16, v16, 10, v42
	v_lshlrev_b32_e32 v182, 4, v40
	v_mov_b32_e32 v183, v177
	v_or_b32_e32 v210, 32, v209
	v_or_b32_e32 v217, 33, v209
	v_or_b32_e32 v218, 2, v209
	v_or_b32_e32 v219, 34, v209
	v_or_b32_e32 v220, 3, v209
	v_or_b32_e32 v221, 35, v209
	v_or_b32_e32 v222, 8, v209
	v_or_b32_e32 v223, 40, v209
	v_or_b32_e32 v224, 9, v209
	v_or_b32_e32 v225, 41, v209
	v_or_b32_e32 v226, 10, v209
	v_or_b32_e32 v227, 42, v209
	v_or_b32_e32 v228, 11, v209
	v_or_b32_e32 v229, 43, v209
	s_waitcnt vmcnt(0)
; #define C_LOADP(p_) do { const bf16_t* q_ = (p_); rka = ldg16(q_ + kvlane); rva = ldg16(q_ + (size_t)16 * T * 64 + kvlane); rkb = ldg16(q_ + (size_t)T * 64 + kvlane); rvb = ldg16(q_ + (size_t)17 * T * 64 + kvlane); } while (0)
; __device__ __forceinline__ void c_phase(const bf16_t* Z, bf16_t* MIX, float* LSE, ldsp lds, int pi, int bx, int G, unsigned& gt, int wave0, int ucount) {
;     ...
;     {   C_DEC(u, b, hp, rs, blk); const int kt0 = blk >= 1 ? 2 * blk - 2 : 0; const bf16_t* kvp = C_KVP(b, hp, rs);
;         C_LOADP(kvp + kt0 * tstride);
;         { const ldsp b0 = lds + (gt & 1u) * 32768; tile_store(b0, rka, rva, key, ch); tile_store(b0 + 16384, rkb, rvb, key, ch); }
;         C_LOADP(kvp + (kt0 + 1) * tstride);
;         __syncthreads(); }
	ds_write_b128 v44, v[20:23]
	v_add3_u32 v20, s1, v204, v205
	s_mov_b32 s1, s13
	v_writelane_b32 v254, s0, 18
	v_add3_u32 v20, v20, v206, v207
	ds_write_b128 v20, v[24:27] offset:8192
	ds_write_b128 v44, v[28:31] offset:16384
	ds_write_b128 v20, v[32:35] offset:24576
	v_writelane_b32 v254, s1, 19
	v_writelane_b32 v254, s2, 20
	v_writelane_b32 v254, s3, 21
	v_writelane_b32 v254, s4, 22
	v_writelane_b32 v254, s5, 23
	v_writelane_b32 v254, s6, 24
	v_writelane_b32 v254, s7, 25
	v_writelane_b32 v254, s8, 26
	v_writelane_b32 v254, s9, 27
	v_writelane_b32 v254, s10, 28
	v_writelane_b32 v254, s11, 29
	v_writelane_b32 v254, s12, 30
	v_writelane_b32 v254, s13, 31
	v_writelane_b32 v254, s14, 32
	v_writelane_b32 v254, s15, 33
	s_lshl_b64 s[0:1], s[12:13], s72
	s_lshl_b64 s[0:1], s[0:1], 1
	s_add_u32 s0, s7, s0
	s_addc_u32 s1, s6, s1
	v_lshl_add_u64 v[20:21], s[0:1], 0, v[36:37]
	v_add_co_u32_e32 v22, vcc, s9, v20
	global_load_dwordx4 v[128:131], v[20:21], off
	s_nop 0
	v_addc_co_u32_e32 v23, vcc, 0, v21, vcc
	global_load_dwordx4 v[132:135], v[22:23], off
	v_add_co_u32_e32 v22, vcc, s10, v20
	s_lshl_b32 s10, s2, 5
	s_nop 0
	v_addc_co_u32_e32 v23, vcc, 0, v21, vcc
	v_add_co_u32_e32 v20, vcc, s11, v20
	global_load_dwordx4 v[136:139], v[22:23], off
	s_nop 0
	v_addc_co_u32_e32 v21, vcc, 0, v21, vcc
	global_load_dwordx4 v[140:143], v[20:21], off
	s_cmp_lg_u32 s38, 0
	s_cselect_b64 s[82:83], -1, 0
	s_cmp_eq_u32 s38, 0
	s_cselect_b64 s[0:1], -1, 0
	v_writelane_b32 v254, s0, 36
	s_add_i32 s9, s31, 13
	s_lshl_b32 s2, 0x2000, s31
	v_writelane_b32 v254, s1, 37
	s_lshl_b32 s0, s30, 14
	s_add_i32 s94, s0, 0
	s_cmp_eq_u32 s38, 1
	v_cmp_gt_u32_e64 s[6:7], 32, v38
	s_cselect_b64 s[0:1], -1, 0
	s_and_b64 s[0:1], s[0:1], s[6:7]
	v_lshl_add_u64 v[20:21], s[80:81], 0, v[176:177]
	v_writelane_b32 v255, s0, 21
	s_mulk_i32 s8, 0x2200
	v_lshl_add_u64 v[188:189], v[20:21], 0, v[186:187]
	v_lshlrev_b32_e32 v20, 4, v17
	v_writelane_b32 v255, s1, 22
	s_add_i32 s0, s8, 0
	v_bitop3_b32 v208, v20, v18, 32 bitop3:0x78
	v_lshlrev_b32_e32 v20, 2, v17
	v_lshlrev_b32_e32 v18, 1, v18
	s_add_i32 s0, s0, 0x10000
	v_and_b32_e32 v247, 32, v18
	v_add_u32_e32 v18, s0, v20
	v_lshl_add_u32 v19, v42, 2, s0
	s_lshl_b64 s[0:1], 1, s9
	v_writelane_b32 v255, s0, 23
	v_writelane_b32 v254, s30, 16
	v_add_u32_e32 v246, s5, v20
	v_writelane_b32 v255, s1, 24
	s_lshl_b64 s[0:1], 2, s9
	v_writelane_b32 v255, s0, 25
	v_mul_u32_u24_e32 v20, 0x440, v43
	v_mul_u32_u24_e32 v21, 0x110, v211
	v_writelane_b32 v255, s1, 26
	s_lshl_b64 s[0:1], 3, s9
	v_writelane_b32 v255, s0, 27
	v_mul_u32_u24_e32 v22, 0x110, v39
	v_lshlrev_b32_e32 v187, 10, v43
	v_writelane_b32 v255, s1, 28
	s_lshl_b64 s[0:1], 0x2000, s31
	v_writelane_b32 v254, s0, 38
	v_writelane_b32 v255, s29, 29
	v_writelane_b32 v255, s4, 30
	v_writelane_b32 v254, s1, 39
	s_lshl_b64 s[0:1], 0x4000, s31
	v_writelane_b32 v254, s0, 34
	v_writelane_b32 v255, s33, 31
	v_or_b32_e32 v230, 16, v209
	v_writelane_b32 v254, s1, 35
	v_writelane_b32 v254, s31, 40
	s_lshl_b64 s[0:1], 0x6000, s31
	v_writelane_b32 v254, s0, 0
	v_or_b32_e32 v231, 48, v209
	v_or_b32_e32 v232, 17, v209
	v_writelane_b32 v254, s1, 1
	s_add_i32 s0, s10, 0xffffff80
	v_or_b32_e32 v233, 49, v209
	v_or_b32_e32 v234, 18, v209
	v_or_b32_e32 v235, 50, v209
	v_or_b32_e32 v236, 19, v209
	v_or_b32_e32 v237, 51, v209
	v_or_b32_e32 v238, 24, v209
	v_or_b32_e32 v239, 56, v209
	v_or_b32_e32 v240, 25, v209
	v_or_b32_e32 v241, 57, v209
	v_or_b32_e32 v242, 26, v209
	v_or_b32_e32 v243, 58, v209
	v_or_b32_e32 v244, 27, v209
	v_or_b32_e32 v245, 59, v209
	v_and_b32_e32 v248, 24, v41
	v_lshlrev_b32_e32 v249, 8, v43
	v_lshl_add_u32 v251, v39, 2, s5
	v_writelane_b32 v254, s10, 41
	v_or_b32_e32 v252, s0, v17
	v_sub_u32_e32 v253, 0, v209
	v_lshlrev_b32_e32 v190, 1, v16
	v_add_u32_e32 v215, v18, v20
	v_add_u32_e32 v178, v18, v21
	v_add_u32_e32 v179, v19, v22
	s_mov_b32 s1, s28
	v_writelane_b32 v255, s35, 32
	s_waitcnt lgkmcnt(0)
	s_mov_b32 s101, 0
	s_mov_b32 s99, 1
	s_barrier

; #define GAS __attribute__((address_space(1)))
; __device__ __forceinline__ void c_phase(const bf16_t* Z, bf16_t* MIX, float* LSE, ldsp lds, int pi, int bx, int G, unsigned& gt, int wave0, int ucount) {
;     ...
;     for (; u < uend; ++u) {
;         C_DEC(u, b, hp, rs, blk);
;         const int head = 2 * hp + hsel, q0 = 128 * blk + 32 * gq, ql = q0 + r32;
;         const int kt0 = blk >= 1 ? 2 * blk - 2 : 0, kt1 = 2 * blk + 1;
;         const bf16_t* kvp = C_KVP(b, hp, rs);
;         const bool has_next = u + 1 < uend;
;         const int un = has_next ? u + 1 : u;
;         C_DEC(un, bn, hpn, rsn, blkn);
;         const int kt0n = blkn >= 1 ? 2 * blkn - 2 : 0;
;         const bf16_t* kvpn = C_KVP(bn, hpn, rsn) + kt0n * tstride;
;         bf16x8 qr[4]; q_load(qr, C_QROW(b, hp, rs, blk), hi);
;         GAS float* lsep = (GAS float*)(LSE + ((size_t)b * T + (size_t)q0 * dil + rs) * 16 + head + llane);
;         bf16_t* orow = MIX + ((size_t)b * T + (size_t)q0 * dil + rs) * 1024 + head * 64 + olane;
;         const size_t ostep = (size_t)8 * dil * 1024;
;         u32x4 orun[4] = {z4, z4, z4, z4}; float lse_old = 0.f;
;         float m = 0.f, l = 0.f; bool started = false;
;         f32x16 o[2], negm; splat16(negm, 0.f);
;         splat16(o[0], 0.f); splat16(o[1], 0.f);
.Lc_qskip:
	s_ashr_i32 s13, s12, 31
	s_lshl_b64 s[12:13], s[12:13], 12
	s_add_u32 s12, s18, s12
	s_addc_u32 s13, s19, s13
	s_lshl_b64 s[16:17], s[12:13], 6
	s_add_u32 s9, s4, s16
	s_addc_u32 s18, s29, s17
	s_ashr_i32 s15, s14, 31
	s_lshl_b64 s[16:17], s[14:15], 2
	s_add_u32 s16, s9, s16
	s_addc_u32 s17, s18, s17
	s_lshl_b64 s[12:13], s[12:13], 11
	v_readlane_b32 s9, v255, 18
	s_add_u32 s9, s9, s12
	v_readlane_b32 s12, v255, 19
	s_addc_u32 s15, s12, s13
	s_lshl_b32 s12, s14, 6
	s_ashr_i32 s13, s12, 31
	s_lshl_b64 s[12:13], s[12:13], 1
	s_add_u32 s12, s9, s12
	s_addc_u32 s13, s15, s13
	s_waitcnt vmcnt(12)
	v_mov_b32_e32 v191, v177
	v_mov_b64_e32 v[62:63], 0
	v_mov_b64_e32 v[46:47], 0
	v_mov_b64_e32 v[30:31], 0
	v_readlane_b32 s37, v254, 19
	v_lshl_add_u64 v[194:195], v[182:183], 2, s[16:17]
	v_lshl_add_u64 v[192:193], s[12:13], 0, v[190:191]
	v_mov_b64_e32 v[60:61], 0
	v_mov_b64_e32 v[58:59], 0
	v_mov_b64_e32 v[56:57], 0
	v_mov_b64_e32 v[54:55], 0
	v_mov_b64_e32 v[52:53], 0
	v_mov_b64_e32 v[50:51], 0
	v_mov_b64_e32 v[48:49], 0
	v_mov_b64_e32 v[44:45], 0
	v_mov_b64_e32 v[42:43], 0
	v_mov_b64_e32 v[40:41], 0
	v_mov_b64_e32 v[38:39], 0
	v_mov_b64_e32 v[36:37], 0
	v_mov_b64_e32 v[34:35], 0
	v_mov_b64_e32 v[32:33], 0
	v_mov_b64_e32 v[28:29], 0
	v_mov_b64_e32 v[26:27], 0
	v_mov_b64_e32 v[24:25], 0
	v_mov_b64_e32 v[22:23], 0
	v_mov_b64_e32 v[20:21], 0
	v_mov_b64_e32 v[18:19], 0
	v_mov_b64_e32 v[16:17], 0
	s_and_b32 s98, s86, s34
	s_lshl_b32 s98, s98, 7
	v_readlane_b32 s100, v254, 41
	s_nop 0
	s_add_i32 s98, s98, s100
	v_readlane_b32 s100, v254, 40
	s_nop 0
	s_lshl_b32 s98, s98, s100
	s_ashr_i32 s100, s86, s33
	s_and_b32 s100, s100, s35
	s_add_i32 s98, s98, s100
	s_lshl_b32 s98, s98, 7
	s_ashr_i32 s100, s86, 8
	s_mul_i32 s100, s100, 48
	s_lshl_b32 s100, s100, 19
	s_add_i32 s98, s98, s100
	s_lshr_b32 s100, s86, 4
	s_and_b32 s100, s100, 14
	s_lshl_b32 s100, s100, 19
	s_add_i32 s98, s98, s100
	v_readlane_b32 s100, v254, 16
	s_nop 0
	s_lshl_b32 s100, s100, 19
	s_add_i32 s98, s98, s100
	s_cmp_gt_i32 s84, s78
	v_readlane_b32 s38, v254, 20
	v_readlane_b32 s39, v254, 21
	v_readlane_b32 s42, v254, 24
	v_readlane_b32 s43, v254, 25
	v_readlane_b32 s44, v254, 26
	v_readlane_b32 s45, v254, 27
	v_readlane_b32 s46, v254, 28
	v_readlane_b32 s47, v254, 29
	v_readlane_b32 s48, v254, 30
	v_readlane_b32 s49, v254, 31
	v_readlane_b32 s50, v254, 32
	v_readlane_b32 s51, v254, 33
	s_cbranch_scc1 .LBB0_1074
	s_add_i32 s0, s11, s0
	s_add_i32 s12, s0, 16
	s_ashr_i32 s13, s12, 31
	s_lshl_b64 s[12:13], s[12:13], 19
	s_add_u32 s0, s80, s12
	s_addc_u32 s9, s81, s13
	s_lshl_b64 s[12:13], s[36:37], 7
	s_add_u32 s85, s0, s12
	s_addc_u32 s0, s9, s13
	s_and_b64 s[12:13], s[40:41], exec
	s_cselect_b32 s1, s86, s1
	s_ashr_i32 s9, s1, 8
	s_lshr_b32 s11, s1, 4
	s_mul_i32 s9, s9, 48
	s_and_b32 s11, s11, 14
	s_or_b32 s9, s9, s11
	s_add_i32 s12, s9, 16
	s_ashr_i32 s13, s12, 31
	s_lshl_b64 s[12:13], s[12:13], 19
	s_add_u32 s9, s80, s12
	s_addc_u32 s11, s81, s13
	s_ashr_i32 s12, s1, s33
	s_and_b32 s12, s12, s35
	s_lshl_b32 s12, s12, 7
	s_add_u32 s9, s9, s12
	s_addc_u32 s11, s11, 0
	s_and_b32 s1, s1, s34
	s_lshl_b32 s12, s1, 1
	s_add_i32 s12, s12, -2
	s_mov_b32 s4, s65
	s_cmp_lg_u32 s1, 0
	s_mov_b32 s1, s37
	s_cselect_b32 s36, s12, 0
	v_writelane_b32 v254, s0, 18
	s_waitcnt vmcnt(8)
	v_mov_b32_e32 v144, 0
	s_mov_b32 s95, s34
	v_writelane_b32 v254, s1, 19
	v_writelane_b32 v254, s2, 20
	v_writelane_b32 v254, s3, 21
	v_writelane_b32 v254, s4, 22
	v_writelane_b32 v254, s5, 23
	v_writelane_b32 v254, s6, 24
	v_writelane_b32 v254, s7, 25
	v_writelane_b32 v254, s8, 26
	v_writelane_b32 v254, s9, 27
	v_writelane_b32 v254, s10, 28
	v_writelane_b32 v254, s11, 29
	v_writelane_b32 v254, s12, 30
	v_writelane_b32 v254, s13, 31
	v_writelane_b32 v254, s14, 32
	v_writelane_b32 v254, s15, 33
	s_lshl_b64 s[12:13], s[36:37], s72
	s_lshl_b64 s[12:13], s[12:13], 1
	s_add_u32 s1, s9, s12
	s_addc_u32 s74, s11, s13
	s_or_b32 s75, s8, 31
	s_add_i32 s76, s8, 0xffffff80
	v_readlane_b32 s8, v255, 23
	v_readlane_b32 s9, v255, 24
	v_add_u32_e32 v64, s10, v252
	s_lshl_b32 s73, s84, 6
	v_lshl_add_u64 v[196:197], s[8:9], 1, v[192:193]
	v_readlane_b32 s8, v255, 25
	v_readlane_b32 s9, v255, 26
	s_lshl_b32 s77, s3, 15
	v_subrev_u32_e32 v213, s73, v64
	v_lshl_add_u64 v[198:199], s[8:9], 1, v[192:193]
	v_readlane_b32 s8, v255, 27
	v_readlane_b32 s9, v255, 28
	s_mov_b64 s[88:89], 0
	v_mov_b32_e32 v191, 0
	v_lshl_add_u64 v[200:201], s[8:9], 1, v[192:193]
	v_mov_b32_e32 v181, 0
	v_mov_b32_e32 v180, 0
	v_mov_b32_e32 v145, v144
	v_mov_b32_e32 v146, v144
	v_mov_b32_e32 v147, v144
	v_mov_b32_e32 v148, v144
	v_mov_b32_e32 v149, v144
	v_mov_b32_e32 v150, v144
	v_mov_b32_e32 v151, v144
	v_mov_b32_e32 v152, v144
	v_mov_b32_e32 v153, v144
	v_mov_b32_e32 v154, v144
	v_mov_b32_e32 v155, v144
	v_mov_b32_e32 v156, v144
	v_mov_b32_e32 v157, v144
	v_mov_b32_e32 v158, v144
	v_mov_b32_e32 v159, v144
	s_cmp_eq_u32 s101, 1
	s_mov_b32 s101, 0
	s_cbranch_scc1 .Lc_pre_deep
	s_waitcnt vmcnt(0)
	s_branch .Lc_pre_join

; #define C_LOADP(p_) do { const bf16_t* q_ = (p_); rka = ldg16(q_ + kvlane); rva = ldg16(q_ + (size_t)16 * T * 64 + kvlane); rkb = ldg16(q_ + (size_t)T * 64 + kvlane); rvb = ldg16(q_ + (size_t)17 * T * 64 + kvlane); } while (0)
; __device__ __forceinline__ void c_phase(const bf16_t* Z, bf16_t* MIX, float* LSE, ldsp lds, int pi, int bx, int G, unsigned& gt, int wave0, int ucount) {
;     ...
;         for (int kt = kt0; kt <= kt1; ++kt) {
;             const ldsp buf = lds + (gt & 1u) * 32768, nxt = lds + ((gt + 1u) & 1u) * 32768;
;             if (kt == kt1 - 1) {
;                 if (pi > 0) { lse_old = *lsep;
; #pragma unroll
;                     for (int i = 0; i < 4; ++i) orun[i] = ldg16(orow + i * ostep); }
;             }
;             if (64 * kt <= q0 + 31 && 64 * kt + 63 >= q0 - 128) {
;                 attn_step(buf + hsel * 16384, buf + hsel * 16384 + 8192, qr, o, m, negm, l, ql - 128 - 64 * kt, ql - 64 * kt, true, !started, wsf, lane, r32, hi); started = true; }
;             if (kt < kt1 || has_next) { tile_store(nxt, rka, rva, key, ch); tile_store(nxt + 16384, rkb, rvb, key, ch); }
;             if (kt + 2 <= kt1) C_LOADP(kvp + (kt + 2) * tstride);
;             else if (has_next) { if (kt == kt1 - 1) C_LOADP(kvpn); else C_LOADP(kvpn + tstride); }
.Lc_pre_join:
.LBB0_1036:
	s_cmp_eq_u32 s87, s84
	s_cselect_b64 s[90:91], -1, 0
	s_and_b32 s99, s99, 1
	s_add_i32 s8, s84, 2
	s_cmp_gt_i32 s8, s78
	s_cbranch_scc1 .Lc_dp_66
	s_ashr_i32 s9, s8, 31
	s_lshl_b64 s[8:9], s[8:9], s72
	s_lshl_b64 s[8:9], s[8:9], 1
	s_add_u32 s8, s85, s8
	s_addc_u32 s9, s0, s9
	s_mov_b64 s[10:11], -1
	s_cbranch_execz .Lc_dp_67
	s_branch .Lc_dp_69

; #define C_LOADP(p_) do { const bf16_t* q_ = (p_); rka = ldg16(q_ + kvlane); rva = ldg16(q_ + (size_t)16 * T * 64 + kvlane); rkb = ldg16(q_ + (size_t)T * 64 + kvlane); rvb = ldg16(q_ + (size_t)17 * T * 64 + kvlane); } while (0)
; __device__ __forceinline__ void c_phase(const bf16_t* Z, bf16_t* MIX, float* LSE, ldsp lds, int pi, int bx, int G, unsigned& gt, int wave0, int ucount) {
;     ...
;             if (kt + 2 <= kt1) C_LOADP(kvp + (kt + 2) * tstride);
;             else if (has_next) { if (kt == kt1 - 1) C_LOADP(kvpn); else C_LOADP(kvpn + tstride); }
.Lc_dp_69:
	s_and_b64 vcc, exec, s[10:11]
	s_cbranch_vccz .Lc_dp_noload
	v_lshl_add_u64 v[64:65], v[184:185], 1, s[8:9]
	v_add_co_u32_e32 v66, vcc, 0x800000, v64
	s_nop 1
	v_addc_co_u32_e32 v67, vcc, 0, v65, vcc
	v_add_co_u32_e32 v68, vcc, 0x80000, v64
	s_nop 1
	v_addc_co_u32_e32 v69, vcc, 0, v65, vcc
	v_add_co_u32_e32 v70, vcc, 0x880000, v64
	s_nop 1
	v_addc_co_u32_e32 v71, vcc, 0, v65, vcc
	s_bitcmp1_b32 s99, 0
	s_cbranch_scc1 .Lc_dp_ld1
	global_load_dwordx4 v[128:131], v[64:65], off
	global_load_dwordx4 v[132:135], v[66:67], off
	global_load_dwordx4 v[136:139], v[68:69], off
	global_load_dwordx4 v[140:143], v[70:71], off
	s_branch .Lc_dp_lddone
.Lc_dp_ld1:
	global_load_dwordx4 v[0:3], v[64:65], off
	global_load_dwordx4 v[4:7], v[66:67], off
	global_load_dwordx4 v[8:11], v[68:69], off
	global_load_dwordx4 v[12:15], v[70:71], off
.Lc_dp_lddone:
	s_or_b32 s99, s99, 2

; #define C_LOADP(p_) do { const bf16_t* q_ = (p_); rka = ldg16(q_ + kvlane); rva = ldg16(q_ + (size_t)16 * T * 64 + kvlane); rkb = ldg16(q_ + (size_t)T * 64 + kvlane); rvb = ldg16(q_ + (size_t)17 * T * 64 + kvlane); } while (0)
; __device__ __forceinline__ void c_phase(const bf16_t* Z, bf16_t* MIX, float* LSE, ldsp lds, int pi, int bx, int G, unsigned& gt, int wave0, int ucount) {
;     ...
;             if (kt < kt1 || has_next) { tile_store(nxt, rka, rva, key, ch); tile_store(nxt + 16384, rkb, rvb, key, ch); }
;             if (kt + 2 <= kt1) C_LOADP(kvp + (kt + 2) * tstride);
;             else if (has_next) { if (kt == kt1 - 1) C_LOADP(kvpn); else C_LOADP(kvpn + tstride); }
;             __syncthreads(); ++gt;
;         }
.LBB0_1062:
	s_cmp_gt_i32 s84, s87
	s_cselect_b64 s[8:9], -1, 0
	s_xor_b64 s[10:11], s[40:41], -1
	s_and_b64 s[8:9], s[10:11], s[8:9]
	s_and_b64 vcc, exec, s[8:9]
	s_cbranch_vccnz .LBB0_1064
	s_xor_b32 s8, s79, 0x8000
	s_add_i32 s8, s8, 0
	v_add3_u32 v64, s8, v202, v203
	v_add3_u32 v65, s8, v204, v205
	v_add3_u32 v65, v65, v206, v207
	s_cmp_eq_u32 s99, 0
	s_cbranch_scc1 .Lc_st_s1_w0
	s_cmp_eq_u32 s99, 2
	s_cbranch_scc1 .Lc_st_s1_w4
	s_cmp_eq_u32 s99, 1
	s_cbranch_scc1 .Lc_st_s0_w0
	s_waitcnt vmcnt(7)
	ds_write_b128 v64, v[128:131]
	s_waitcnt vmcnt(6)
	ds_write_b128 v65, v[132:135] offset:8192
	s_waitcnt vmcnt(5)
	ds_write_b128 v64, v[136:139] offset:16384
	s_waitcnt vmcnt(4)
	ds_write_b128 v65, v[140:143] offset:24576
	s_branch .LBB0_1064
.Lc_st_s0_w0:
	s_waitcnt vmcnt(3)
	ds_write_b128 v64, v[128:131]
	s_waitcnt vmcnt(2)
	ds_write_b128 v65, v[132:135] offset:8192
	s_waitcnt vmcnt(1)
	ds_write_b128 v64, v[136:139] offset:16384
	s_waitcnt vmcnt(0)
	ds_write_b128 v65, v[140:143] offset:24576
	s_branch .LBB0_1064
.Lc_st_s1_w4:
	s_waitcnt vmcnt(7)
	ds_write_b128 v64, v[0:3]
	s_waitcnt vmcnt(6)
	ds_write_b128 v65, v[4:7] offset:8192
	s_waitcnt vmcnt(5)
	ds_write_b128 v64, v[8:11] offset:16384
	s_waitcnt vmcnt(4)
	ds_write_b128 v65, v[12:15] offset:24576
	s_branch .LBB0_1064
.Lc_st_s1_w0:
	s_waitcnt vmcnt(3)
	ds_write_b128 v64, v[0:3]
	s_waitcnt vmcnt(2)
	ds_write_b128 v65, v[4:7] offset:8192
	s_waitcnt vmcnt(1)
	ds_write_b128 v64, v[8:11] offset:16384
	s_waitcnt vmcnt(0)
	ds_write_b128 v65, v[12:15] offset:24576
	s_branch .LBB0_1064
.LBB0_1064:
.LBB0_1071:
	s_xor_b32 s99, s99, 1
	s_add_i32 s3, s3, 1
	s_add_i32 s77, s77, 0x8000
	s_add_i32 s73, s73, 64
	s_add_i32 s8, s84, 1
	s_cmp_gt_i32 s84, s87
	v_subrev_u32_e32 v213, 64, v213
	s_waitcnt lgkmcnt(0)
	s_barrier
	s_cbranch_scc1 .LBB0_1075
	s_mov_b32 s84, s8
	s_branch .LBB0_1036

; __device__ __forceinline__ void c_phase(const bf16_t* Z, bf16_t* MIX, float* LSE, ldsp lds, int pi, int bx, int G, unsigned& gt, int wave0, int ucount) {
;     ...
;         const bool has_next = u + 1 < uend;
;         const int un = has_next ? u + 1 : u;
;         C_DEC(un, bn, hpn, rsn, blkn);
;         const int kt0n = blkn >= 1 ? 2 * blkn - 2 : 0;
;         const bf16_t* kvpn = C_KVP(bn, hpn, rsn) + kt0n * tstride;
;         bf16x8 qr[4]; q_load(qr, C_QROW(b, hp, rs, blk), hi);
.LBB0_1076:
	s_and_b64 vcc, exec, s[40:41]
	s_cbranch_vccz .Lc_qpre_skip
	v_mov_b32_e32 v64, s98
	v_mov_b32_e32 v65, 0
	v_lshl_add_u64 v[64:65], v[188:189], 0, v[64:65]
	global_load_dwordx4 v[160:163], v[64:65], off
	global_load_dwordx4 v[164:167], v[64:65], off offset:32
	global_load_dwordx4 v[168:171], v[64:65], off offset:64
	global_load_dwordx4 v[172:175], v[64:65], off offset:96
	s_mov_b32 s101, 1
